# diff-attention item setup de-serialisation: bias-table loads waited with a counted vmcnt after the Q loads are issued
# baseline (speedup 1.0000x reference)
.LBB0_1220:
	s_and_saveexec_b64 s[38:39], s[6:7]
	s_cbranch_execz .LBB0_1222
	v_or_b32_e32 v2, s40, v127
	s_or_b32 s54, s40, s4
	v_ashrrev_i32_e32 v3, 31, v2
	s_lshl_b64 vcc, s[54:55], 2
	v_lshl_add_u64 v[2:3], v[2:3], 2, s[14:15]
	s_add_u32 vcc_lo, s14, vcc_lo
	s_addc_u32 vcc_hi, s15, vcc_hi
	global_load_dword v250, v[2:3], off
	s_nop 0
	global_load_dword v251, v1, vcc offset:1984
.LBB0_1222:
	s_or_b64 exec, exec, s[38:39]
	s_lshl_b32 s54, s40, 7
	v_lshl_add_u64 v[14:15], v[130:131], 0, s[54:55]
	global_load_dwordx4 v[224:227], v[14:15], off
	global_load_dwordx4 v[228:231], v[14:15], off offset:32
	global_load_dwordx4 v[232:235], v[14:15], off offset:64
	global_load_dwordx4 v[236:239], v[14:15], off offset:96
	s_and_saveexec_b64 s[96:97], s[6:7]
	s_waitcnt vmcnt(4)
	v_sub_f32_e32 v250, v250, v251
	v_mul_f32_e32 v250, 0x3fb8aa3b, v250
	ds_write_b32 v168, v250
	s_or_b64 exec, exec, s[96:97]
	s_lshl_b32 s38, s40, 19
	s_or_b32 s38, s38, s94
	s_add_u32 s40, s12, s38
	s_addc_u32 s41, s13, 0
	s_add_u32 s38, s40, s30
	s_addc_u32 s39, s41, s31
	v_lshl_add_u64 v[18:19], v[116:117], 1, s[38:39]
	s_andn2_b64 vcc, exec, s[22:23]
	s_mov_b32 s38, m0
	s_mov_b32 m0, s81
	s_nop 0
	global_load_lds_dwordx4 v[18:19], off
	s_mov_b32 m0, s38
	s_nop 0
	s_mov_b32 s38, m0
	s_mov_b32 m0, s84
	s_nop 0
	global_load_lds_dwordx4 v[132:133], off
	s_mov_b32 m0, s38
	s_nop 0
	s_mov_b32 s38, m0
	s_mov_b32 m0, s86
	s_nop 0
	global_load_lds_dwordx4 v[134:135], off
	s_mov_b32 m0, s38
	s_cbranch_vccnz .LBB0_1224
	s_add_u32 s38, s40, s34
	s_addc_u32 s39, s41, s35
	v_lshl_add_u64 v[2:3], v[116:117], 1, s[38:39]
	s_mov_b32 s38, m0
	s_mov_b32 m0, s87
	s_nop 0
	global_load_lds_dwordx4 v[2:3], off
	s_mov_b32 m0, s38
	s_nop 0
	s_mov_b32 s38, m0
	s_mov_b32 m0, s88
	s_nop 0
	global_load_lds_dwordx4 v[136:137], off
	s_mov_b32 m0, s38
	s_nop 0
	s_mov_b32 s38, m0
	s_mov_b32 m0, s89
	s_nop 0
	global_load_lds_dwordx4 v[138:139], off
	s_mov_b32 m0, s38
